# v41 plus stacked NA issue-slot reductions: next-group K-fragment read-ahead and add + v_cndmask select instead of exec save/restore
# speedup vs baseline: 1.0048x; 1.0048x over previous
; #define LAS __attribute__((address_space(3)))
; #define MFMA32(a, b, c) __builtin_amdgcn_mfma_f32_16x16x32_bf16((a), (b), (c), 0, 0, 0)
; DI void na_phase(LAS unsigned char* lds, const Args& A, const bf16* proj, bf16* nao, int T, int nB, unsigned* counter, int tid_in) {
;     ...
;             for (int rr = 0; rr < 4; ++rr) { const int kr = rs + 4 * kh + rr, sl = kr & 7;
; #pragma unroll
;                 for (int ct = 0; ct < 2; ++ct) { const int cm = cs0 + 16 * ct + l15; f32x4 acc = (f32x4){0.f, 0.f, 0.f, 0.f};
; #pragma unroll
;                     for (int ks = 0; ks < 2; ++ks) { const bf16x8 kf = *(const LAS bf16x8*)(lds + NA_K + sl * 8192 + cm * 128 + (((4 * ks + g) ^ ((cm >> 1) & 7)) * 16)); acc = MFMA32(kf, qf[ks], acc); }
; #pragma unroll
;                     for (int e = 0; e < 4; ++e) { const int cc = cs0 + 16 * ct + 4 * g + e; const bool valid = (cc >= csq) && (cc < csq + 16);
;                         const int bi = (kr - r + 7) * 31 + min(max(cc - cq + 15, 0), 30);
;                         const float sv = valid ? acc[e] + BI[bi] : -INFINITY; acc[e] = sv; mx = fmaxf(mx, sv); }
;                     sT[rr][ct] = acc; } }
.LBB0_337:
	v_add_u32_e32 v31, s38, v71
	v_lshlrev_b32_e32 v24, 13, v31
	v_and_b32_e32 v28, 0xe000, v24
	v_add_u32_e32 v30, 0, v28
	v_add_u32_e32 v29, v30, v91
	v_add_u32_e32 v24, v29, v92
	ds_read_b128 v[24:27], v24
	v_add_u32_e32 v29, v29, v93
	ds_read_b128 v[58:61], v29
	s_add_i32 s0, s19, s38
	v_add_u32_e32 v29, s0, v57
	v_mul_lo_u32 v29, v29, s88
	v_add_u32_e32 v38, s87, v29
	v_add_u32_e32 v29, 0xfffff080, v38
	v_mov_b32_e32 v63, 0xff800000
	v_lshl_add_u32 v252, v94, 2, v29
	ds_read_b32 v252, v252 offset:868
	v_lshl_add_u32 v253, v95, 2, v29
	ds_read_b32 v253, v253 offset:868
	v_lshl_add_u32 v254, v96, 2, v29
	ds_read_b32 v254, v254 offset:868
	v_lshl_add_u32 v255, v97, 2, v29
	ds_read_b32 v255, v255 offset:868
	v_add_u32_e32 v30, v30, v98
	v_add_u32_e32 v156, v30, v92
	ds_read_b128 v[140:143], v156
	v_add_u32_e32 v30, v30, v93
	ds_read_b128 v[144:147], v30
	s_waitcnt lgkmcnt(7)
	v_mfma_f32_16x16x32_bf16 v[24:27], v[24:27], v[20:23], 0
	s_waitcnt lgkmcnt(6)
	v_mfma_f32_16x16x32_bf16 v[24:27], v[58:61], v[16:19], v[24:27]
	v_mov_b32_e32 v59, 0xff800000
	s_waitcnt lgkmcnt(2)
	s_nop 6
	v_add_f32_e32 v252, v24, v252
	v_cndmask_b32_e64 v63, v63, v252, s[14:15]
	v_add_f32_e32 v253, v25, v253
	v_cndmask_b32_e64 v59, v59, v253, s[16:17]
	v_mov_b32_e32 v56, 0xff800000
	v_mov_b32_e32 v62, 0xff800000
	v_add_f32_e32 v254, v26, v254
	v_cndmask_b32_e64 v62, v62, v254, s[48:49]
	v_add_f32_e32 v255, v27, v255
	v_cndmask_b32_e64 v56, v56, v255, s[50:51]
	v_mov_b32_e32 v39, 0xff800000
	v_lshl_add_u32 v252, v99, 2, v29
	ds_read_b32 v252, v252 offset:868
	v_lshl_add_u32 v253, v100, 2, v29
	ds_read_b32 v253, v253 offset:868
	v_lshl_add_u32 v254, v101, 2, v29
	ds_read_b32 v254, v254 offset:868
	v_lshl_add_u32 v255, v102, 2, v29
	ds_read_b32 v255, v255 offset:868
	v_lshl_add_u32 v156, v31, 13, v212
	v_and_b32_e32 v29, 0xe000, v156
	v_add_u32_e32 v66, 0, v29
	v_add_u32_e32 v30, v66, v91
	v_add_u32_e32 v156, v30, v92
	ds_read_b128 v[148:151], v156
	v_add_u32_e32 v30, v30, v93
	ds_read_b128 v[152:155], v30
	s_waitcnt lgkmcnt(7)
	v_mfma_f32_16x16x32_bf16 v[24:27], v[140:143], v[20:23], 0
	s_waitcnt lgkmcnt(6)
	v_mfma_f32_16x16x32_bf16 v[24:27], v[144:147], v[16:19], v[24:27]
	v_mov_b32_e32 v65, 0xff800000
	s_waitcnt lgkmcnt(2)
	s_nop 6
	v_add_f32_e32 v252, v24, v252
	v_cndmask_b32_e64 v65, v65, v252, s[52:53]
	v_add_f32_e32 v253, v25, v253
	v_cndmask_b32_e64 v39, v39, v253, s[56:57]
	v_mov_b32_e32 v54, 0xff800000
	v_mov_b32_e32 v55, 0xff800000
	v_add_f32_e32 v254, v26, v254
	v_cndmask_b32_e64 v55, v55, v254, s[76:77]
	v_add_f32_e32 v255, v27, v255
	v_cndmask_b32_e64 v54, v54, v255, s[66:67]
	v_add_u32_e32 v30, 0xfffff0fc, v38
	v_mov_b32_e32 v58, 0xff800000
	v_mov_b32_e32 v60, 0xff800000
	v_lshl_add_u32 v252, v94, 2, v30
	ds_read_b32 v252, v252 offset:868
	v_lshl_add_u32 v253, v95, 2, v30
	ds_read_b32 v253, v253 offset:868
	v_lshl_add_u32 v254, v96, 2, v30
	ds_read_b32 v254, v254 offset:868
	v_lshl_add_u32 v255, v97, 2, v30
	ds_read_b32 v255, v255 offset:868
	v_add_u32_e32 v66, v66, v98
	v_add_u32_e32 v156, v66, v92
	ds_read_b128 v[140:143], v156
	v_add_u32_e32 v66, v66, v93
	ds_read_b128 v[144:147], v66
	s_waitcnt lgkmcnt(7)
	v_mfma_f32_16x16x32_bf16 v[24:27], v[148:151], v[20:23], 0
	s_waitcnt lgkmcnt(6)
	v_mfma_f32_16x16x32_bf16 v[24:27], v[152:155], v[16:19], v[24:27]
	s_waitcnt lgkmcnt(2)
	s_nop 6
	v_add_f32_e32 v252, v24, v252
	v_cndmask_b32_e64 v60, v60, v252, s[14:15]
	v_add_f32_e32 v253, v25, v253
	v_cndmask_b32_e64 v58, v58, v253, s[16:17]
	v_mov_b32_e32 v61, 0xff800000
	v_mov_b32_e32 v64, 0xff800000
	v_add_f32_e32 v254, v26, v254
	v_cndmask_b32_e64 v64, v64, v254, s[48:49]
	v_add_f32_e32 v255, v27, v255
	v_cndmask_b32_e64 v61, v61, v255, s[50:51]
	v_mov_b32_e32 v66, 0xff800000
	v_mov_b32_e32 v67, 0xff800000
	v_lshl_add_u32 v252, v99, 2, v30
	ds_read_b32 v252, v252 offset:868
	v_lshl_add_u32 v253, v100, 2, v30
	ds_read_b32 v253, v253 offset:868
	v_lshl_add_u32 v254, v101, 2, v30
	ds_read_b32 v254, v254 offset:868
	v_lshl_add_u32 v255, v102, 2, v30
	ds_read_b32 v255, v255 offset:868
	v_lshl_add_u32 v156, v31, 13, v213
	v_and_b32_e32 v30, 0xe000, v156
	v_add_u32_e32 v110, 0, v30
	v_add_u32_e32 v106, v110, v91
	v_add_u32_e32 v156, v106, v92
	ds_read_b128 v[148:151], v156
	v_add_u32_e32 v106, v106, v93
	ds_read_b128 v[152:155], v106
	s_waitcnt lgkmcnt(7)
	v_mfma_f32_16x16x32_bf16 v[24:27], v[140:143], v[20:23], 0
	s_waitcnt lgkmcnt(6)
	v_mfma_f32_16x16x32_bf16 v[24:27], v[144:147], v[16:19], v[24:27]
	s_waitcnt lgkmcnt(2)
	s_nop 6
	v_add_f32_e32 v252, v24, v252
	v_cndmask_b32_e64 v67, v67, v252, s[52:53]
	v_add_f32_e32 v253, v25, v253
	v_cndmask_b32_e64 v66, v66, v253, s[56:57]
	v_mov_b32_e32 v104, 0xff800000
	v_mov_b32_e32 v105, 0xff800000
	v_add_f32_e32 v254, v26, v254
	v_cndmask_b32_e64 v105, v105, v254, s[76:77]
	v_add_f32_e32 v255, v27, v255
	v_cndmask_b32_e64 v104, v104, v255, s[66:67]
	v_add_u32_e32 v114, 0xfffff178, v38
	v_lshl_add_u32 v252, v94, 2, v114
	ds_read_b32 v252, v252 offset:868
	v_lshl_add_u32 v253, v95, 2, v114
	ds_read_b32 v253, v253 offset:868
	v_lshl_add_u32 v254, v96, 2, v114
	ds_read_b32 v254, v254 offset:868
	v_lshl_add_u32 v255, v97, 2, v114
	ds_read_b32 v255, v255 offset:868
	v_add_u32_e32 v110, v110, v98
	v_add_u32_e32 v156, v110, v92
	ds_read_b128 v[140:143], v156
	v_add_u32_e32 v110, v110, v93
	ds_read_b128 v[144:147], v110
	s_waitcnt lgkmcnt(7)
	v_mfma_f32_16x16x32_bf16 v[24:27], v[148:151], v[20:23], 0
	s_waitcnt lgkmcnt(6)
	v_mfma_f32_16x16x32_bf16 v[24:27], v[152:155], v[16:19], v[24:27]
	v_mov_b32_e32 v106, 0xff800000
	v_mov_b32_e32 v107, 0xff800000
	s_waitcnt lgkmcnt(2)
; #define LAS __attribute__((address_space(3)))
; #define MFMA32(a, b, c) __builtin_amdgcn_mfma_f32_16x16x32_bf16((a), (b), (c), 0, 0, 0)
; DI void na_phase(LAS unsigned char* lds, const Args& A, const bf16* proj, bf16* nao, int T, int nB, unsigned* counter, int tid_in) {
;     ...
;             for (int rr = 0; rr < 4; ++rr) { const int kr = rs + 4 * kh + rr, sl = kr & 7;
; #pragma unroll
;                 for (int ct = 0; ct < 2; ++ct) { const int cm = cs0 + 16 * ct + l15; f32x4 acc = (f32x4){0.f, 0.f, 0.f, 0.f};
; #pragma unroll
;                     for (int ks = 0; ks < 2; ++ks) { const bf16x8 kf = *(const LAS bf16x8*)(lds + NA_K + sl * 8192 + cm * 128 + (((4 * ks + g) ^ ((cm >> 1) & 7)) * 16)); acc = MFMA32(kf, qf[ks], acc); }
; #pragma unroll
;                     for (int e = 0; e < 4; ++e) { const int cc = cs0 + 16 * ct + 4 * g + e; const bool valid = (cc >= csq) && (cc < csq + 16);
;                         const int bi = (kr - r + 7) * 31 + min(max(cc - cq + 15, 0), 30);
;                         const float sv = valid ? acc[e] + BI[bi] : -INFINITY; acc[e] = sv; mx = fmaxf(mx, sv); }
;                     sT[rr][ct] = acc; } }
;             mx = fmaxf(mx, __shfl_xor(mx, 16)); mx = fmaxf(mx, __shfl_xor(mx, 32));
;             float lsum = 0.f;
; #pragma unroll
;             for (int rr = 0; rr < 4; ++rr)
; #pragma unroll
;                 for (int ct = 0; ct < 2; ++ct)
; #pragma unroll
;                     for (int e = 0; e < 4; ++e) { const float p = __expf(sT[rr][ct][e] - mx); sT[rr][ct][e] = p; lsum += p; }
	s_nop 6
	v_add_f32_e32 v252, v24, v252
	v_cndmask_b32_e64 v107, v107, v252, s[14:15]
	v_add_f32_e32 v253, v25, v253
	v_cndmask_b32_e64 v106, v106, v253, s[16:17]
	v_mov_b32_e32 v108, 0xff800000
	v_mov_b32_e32 v109, 0xff800000
	v_add_f32_e32 v254, v26, v254
	v_cndmask_b32_e64 v109, v109, v254, s[48:49]
	v_add_f32_e32 v255, v27, v255
	v_cndmask_b32_e64 v108, v108, v255, s[50:51]
	v_lshl_add_u32 v252, v99, 2, v114
	ds_read_b32 v252, v252 offset:868
	v_lshl_add_u32 v253, v100, 2, v114
	ds_read_b32 v253, v253 offset:868
	v_lshl_add_u32 v254, v101, 2, v114
	ds_read_b32 v254, v254 offset:868
	v_lshl_add_u32 v255, v102, 2, v114
	ds_read_b32 v255, v255 offset:868
	v_lshl_add_u32 v156, v31, 13, v214
	v_and_b32_e32 v31, 0xe000, v156
	v_add_u32_e32 v116, 0, v31
	v_add_u32_e32 v114, v116, v91
	v_add_u32_e32 v156, v114, v92
	ds_read_b128 v[148:151], v156
	v_add_u32_e32 v114, v114, v93
	ds_read_b128 v[152:155], v114
	s_waitcnt lgkmcnt(7)
	v_mfma_f32_16x16x32_bf16 v[24:27], v[140:143], v[20:23], 0
	s_waitcnt lgkmcnt(6)
	v_mfma_f32_16x16x32_bf16 v[24:27], v[144:147], v[16:19], v[24:27]
	v_mov_b32_e32 v110, 0xff800000
	v_mov_b32_e32 v111, 0xff800000
	s_waitcnt lgkmcnt(2)
	s_nop 6
	v_add_f32_e32 v252, v24, v252
	v_cndmask_b32_e64 v111, v111, v252, s[52:53]
	v_add_f32_e32 v253, v25, v253
	v_cndmask_b32_e64 v110, v110, v253, s[56:57]
	v_mov_b32_e32 v112, 0xff800000
	v_mov_b32_e32 v113, 0xff800000
	v_add_f32_e32 v254, v26, v254
	v_cndmask_b32_e64 v113, v113, v254, s[76:77]
	v_add_f32_e32 v255, v27, v255
	v_cndmask_b32_e64 v112, v112, v255, s[66:67]
	v_add_u32_e32 v38, 0xfffff1f4, v38
	v_mov_b32_e32 v114, 0xff800000
	v_mov_b32_e32 v115, 0xff800000
	v_lshl_add_u32 v252, v94, 2, v38
	ds_read_b32 v252, v252 offset:868
	v_lshl_add_u32 v253, v95, 2, v38
	ds_read_b32 v253, v253 offset:868
	s_waitcnt lgkmcnt(3)
	v_mfma_f32_16x16x32_bf16 v[24:27], v[148:151], v[20:23], 0
	s_waitcnt lgkmcnt(2)
	v_mfma_f32_16x16x32_bf16 v[24:27], v[152:155], v[16:19], v[24:27]
	s_waitcnt lgkmcnt(0)
	s_nop 6
	v_add_f32_e32 v252, v24, v252
	v_cndmask_b32_e64 v115, v115, v252, s[14:15]
	v_add_f32_e32 v253, v25, v253
	v_cndmask_b32_e64 v114, v114, v253, s[16:17]
	s_nop 1
	v_mov_b32_e32 v24, 0xff800000
	v_mov_b32_e32 v25, 0xff800000
	v_lshl_add_u32 v252, v96, 2, v38
	ds_read_b32 v252, v252 offset:868
	v_lshl_add_u32 v253, v97, 2, v38
	ds_read_b32 v253, v253 offset:868
	s_waitcnt lgkmcnt(0)
	s_nop 2
	v_add_f32_e32 v252, v26, v252
	v_cndmask_b32_e64 v25, v25, v252, s[48:49]
	v_add_f32_e32 v253, v27, v253
	v_cndmask_b32_e64 v24, v24, v253, s[50:51]
	v_add_u32_e32 v26, v116, v98
	v_add_u32_e32 v27, v26, v92
	ds_read_b128 v[116:119], v27
	v_add_u32_e32 v26, v26, v93
	s_waitcnt lgkmcnt(0)
	v_mfma_f32_16x16x32_bf16 v[20:23], v[116:119], v[20:23], 0
	ds_read_b128 v[116:119], v26
	s_waitcnt lgkmcnt(0)
	v_mfma_f32_16x16x32_bf16 v[16:19], v[116:119], v[16:19], v[20:23]
	s_nop 4
	v_mov_b32_e32 v20, 0xff800000
	v_mov_b32_e32 v21, 0xff800000
	v_lshl_add_u32 v252, v99, 2, v38
	ds_read_b32 v252, v252 offset:868
	v_lshl_add_u32 v253, v100, 2, v38
	ds_read_b32 v253, v253 offset:868
	v_lshl_add_u32 v254, v101, 2, v38
	ds_read_b32 v254, v254 offset:868
	v_lshl_add_u32 v255, v102, 2, v38
	ds_read_b32 v255, v255 offset:868
	s_waitcnt lgkmcnt(0)
	v_add_f32_e32 v252, v16, v252
	v_cndmask_b32_e64 v21, v21, v252, s[52:53]
	v_add_f32_e32 v253, v17, v253
	v_cndmask_b32_e64 v20, v20, v253, s[56:57]
	v_mov_b32_e32 v16, 0xff800000
	v_mov_b32_e32 v17, 0xff800000
	v_add_f32_e32 v254, v18, v254
	v_cndmask_b32_e64 v17, v17, v254, s[76:77]
	v_add_f32_e32 v255, v19, v255
	v_cndmask_b32_e64 v16, v16, v255, s[66:67]
	v_max3_f32 v18, v63, s89, v59
	v_max3_f32 v18, v18, v62, v56
	v_max3_f32 v18, v18, v65, v39
	v_max3_f32 v18, v18, v55, v54
	v_max3_f32 v18, v18, v60, v58
	v_max3_f32 v18, v18, v64, v61
	v_max3_f32 v18, v18, v67, v66
	v_max3_f32 v18, v18, v105, v104
	v_max3_f32 v18, v18, v107, v106
	v_max3_f32 v18, v18, v109, v108
	v_max3_f32 v18, v18, v111, v110
	v_max3_f32 v18, v18, v113, v112
	v_max3_f32 v18, v18, v115, v114
	v_max3_f32 v18, v18, v25, v24
	v_max3_f32 v18, v18, v21, v20
	v_max3_f32 v18, v18, v17, v16
	v_mov_b32_e32 v19, v18
	s_nop 1
	v_permlane16_swap_b32_e32 v19, v18
	v_max_f32_e32 v18, v18, v19
	v_mov_b32_e32 v19, v18
	s_nop 1
	v_permlane32_swap_b32_e32 v19, v18
	v_max_f32_e32 v38, v18, v19
	v_sub_f32_e32 v39, v39, v38
	v_mul_f32_e32 v39, 0x3fb8aa3b, v39
	v_sub_f32_e32 v26, v56, v38
	v_exp_f32_e32 v56, v39
	v_sub_f32_e32 v39, v55, v38
	v_mul_f32_e32 v39, 0x3fb8aa3b, v39
	v_exp_f32_e32 v55, v39
	v_sub_f32_e32 v39, v54, v38
	v_mul_f32_e32 v39, 0x3fb8aa3b, v39
	v_sub_f32_e32 v22, v59, v38
	v_exp_f32_e32 v59, v39
	v_sub_f32_e32 v39, v60, v38
	v_mul_f32_e32 v39, 0x3fb8aa3b, v39
	v_exp_f32_e32 v116, v39
	v_sub_f32_e32 v39, v58, v38
	v_mul_f32_e32 v39, 0x3fb8aa3b, v39
	v_exp_f32_e32 v117, v39
	v_sub_f32_e32 v39, v64, v38
	v_mul_f32_e32 v39, 0x3fb8aa3b, v39
	v_exp_f32_e32 v118, v39
	v_sub_f32_e32 v39, v61, v38
	v_mul_f32_e32 v39, 0x3fb8aa3b, v39
	v_exp_f32_e32 v119, v39
	v_sub_f32_e32 v39, v67, v38
	v_sub_f32_e32 v18, v63, v38
	v_mul_f32_e32 v39, 0x3fb8aa3b, v39
	v_mul_f32_e32 v18, 0x3fb8aa3b, v18
	v_exp_f32_e32 v67, v39
	v_sub_f32_e32 v39, v66, v38
	v_exp_f32_e32 v18, v18
	v_mul_f32_e32 v22, 0x3fb8aa3b, v22
	v_sub_f32_e32 v23, v62, v38
	v_mul_f32_e32 v39, 0x3fb8aa3b, v39
	v_exp_f32_e32 v22, v22
	v_mul_f32_e32 v23, 0x3fb8aa3b, v23
	v_exp_f32_e32 v66, v39
	v_sub_f32_e32 v39, v105, v38
	v_exp_f32_e32 v23, v23
	v_mul_f32_e32 v26, 0x3fb8aa3b, v26
	v_sub_f32_e32 v27, v65, v38
	v_mul_f32_e32 v39, 0x3fb8aa3b, v39
	v_exp_f32_e32 v26, v26
	v_mul_f32_e32 v27, 0x3fb8aa3b, v27
	v_exp_f32_e32 v120, v39
	v_sub_f32_e32 v39, v104, v38
; #define LAS __attribute__((address_space(3)))
; DI unsigned pk2(float lo, float hi) { f32x2 v = {lo, hi}; bf16v2 b = __builtin_convertvector(v, bf16v2); return __builtin_bit_cast(unsigned, b); }
; #define MFMA32(a, b, c) __builtin_amdgcn_mfma_f32_16x16x32_bf16((a), (b), (c), 0, 0, 0)
; DI void na_phase(LAS unsigned char* lds, const Args& A, const bf16* proj, bf16* nao, int T, int nB, unsigned* counter, int tid_in) {
;     ...
;             float lsum = 0.f;
; #pragma unroll
;             for (int rr = 0; rr < 4; ++rr)
; #pragma unroll
;                 for (int ct = 0; ct < 2; ++ct)
; #pragma unroll
;                     for (int e = 0; e < 4; ++e) { const float p = __expf(sT[rr][ct][e] - mx); sT[rr][ct][e] = p; lsum += p; }
;             lsum += __shfl_xor(lsum, 16); lsum += __shfl_xor(lsum, 32);
;             f32x4 O[4];
; #pragma unroll
;             for (int mt = 0; mt < 4; ++mt) O[mt] = (f32x4){0.f, 0.f, 0.f, 0.f};
; #pragma unroll
;             for (int rr = 0; rr < 4; ++rr) { const int sl = (rs + 4 * kh + rr) & 7;
;                 const u32x4 pw = (u32x4){pk2(sT[rr][0][0], sT[rr][0][1]), pk2(sT[rr][0][2], sT[rr][0][3]), pk2(sT[rr][1][0], sT[rr][1][1]), pk2(sT[rr][1][2], sT[rr][1][3])};
;                 const bf16x8 pb = __builtin_bit_cast(bf16x8, pw);
; #pragma unroll
;                 for (int mt = 0; mt < 4; ++mt) { const int dd = 16 * mt + l15, sw = 2 * ((dd >> 1) & 7);
;                     const LAS unsigned char* vb = lds + NA_V + sl * 8192 + dd * 128;
;                     const u32x2 lo = *(const LAS u32x2*)(vb + ((((cs0 >> 2) + g) ^ sw) * 8)), hi = *(const LAS u32x2*)(vb + ((((cs0 >> 2) + 4 + g) ^ sw) * 8));
;                     const u32x4 vv = (u32x4){lo.x, lo.y, hi.x, hi.y};
;                     O[mt] = MFMA32(__builtin_bit_cast(bf16x8, vv), pb, O[mt]); } }
;             LAS float* MG = (LAS float*)(lds + NA_MRG + qg * 4608) + lane;
;             if (kh == 1) { MG[0] = mx; MG[64] = lsum;
	v_add_f32_e32 v19, 0, v18
	v_exp_f32_e32 v27, v27
	v_mul_f32_e32 v39, 0x3fb8aa3b, v39
	v_add_f32_e32 v19, v22, v19
	v_exp_f32_e32 v121, v39
	v_sub_f32_e32 v39, v107, v38
	v_add_f32_e32 v19, v23, v19
	v_mul_f32_e32 v39, 0x3fb8aa3b, v39
	v_add_f32_e32 v19, v26, v19
	v_exp_f32_e32 v122, v39
	v_sub_f32_e32 v39, v106, v38
	v_add_f32_e32 v19, v27, v19
	v_mul_f32_e32 v39, 0x3fb8aa3b, v39
	v_add_f32_e32 v19, v56, v19
	v_exp_f32_e32 v123, v39
	v_sub_f32_e32 v39, v109, v38
	v_add_f32_e32 v19, v55, v19
	v_mul_f32_e32 v39, 0x3fb8aa3b, v39
	v_add_f32_e32 v19, v59, v19
	v_exp_f32_e32 v124, v39
	v_sub_f32_e32 v39, v108, v38
	v_add_f32_e32 v19, v116, v19
	v_mul_f32_e32 v39, 0x3fb8aa3b, v39
	v_add_f32_e32 v19, v117, v19
	v_exp_f32_e32 v125, v39
	v_sub_f32_e32 v39, v111, v38
	v_add_f32_e32 v19, v118, v19
	v_mul_f32_e32 v39, 0x3fb8aa3b, v39
	v_add_f32_e32 v19, v119, v19
	v_exp_f32_e32 v126, v39
	v_sub_f32_e32 v39, v110, v38
	v_add_f32_e32 v19, v67, v19
	v_mul_f32_e32 v39, 0x3fb8aa3b, v39
	v_add_f32_e32 v19, v66, v19
	v_exp_f32_e32 v127, v39
	v_sub_f32_e32 v39, v113, v38
	v_add_f32_e32 v19, v120, v19
	v_mul_f32_e32 v39, 0x3fb8aa3b, v39
	v_add_f32_e32 v19, v121, v19
	v_exp_f32_e32 v128, v39
	v_sub_f32_e32 v39, v112, v38
	v_add_f32_e32 v19, v122, v19
	v_mul_f32_e32 v39, 0x3fb8aa3b, v39
	v_add_f32_e32 v19, v123, v19
	v_exp_f32_e32 v129, v39
	v_sub_f32_e32 v39, v115, v38
	v_add_f32_e32 v19, v124, v19
	v_mul_f32_e32 v39, 0x3fb8aa3b, v39
	v_add_f32_e32 v19, v125, v19
	v_exp_f32_e32 v130, v39
	v_sub_f32_e32 v39, v114, v38
	v_add_f32_e32 v19, v126, v19
	v_mul_f32_e32 v39, 0x3fb8aa3b, v39
	v_sub_f32_e32 v25, v25, v38
	v_add_f32_e32 v19, v127, v19
	v_exp_f32_e32 v131, v39
	v_mul_f32_e32 v25, 0x3fb8aa3b, v25
	v_sub_f32_e32 v24, v24, v38
	v_add_f32_e32 v19, v128, v19
	v_exp_f32_e32 v132, v25
	v_mul_f32_e32 v24, 0x3fb8aa3b, v24
	v_sub_f32_e32 v21, v21, v38
	v_add_f32_e32 v19, v129, v19
	v_exp_f32_e32 v133, v24
	v_mul_f32_e32 v21, 0x3fb8aa3b, v21
	v_sub_f32_e32 v20, v20, v38
	v_add_f32_e32 v19, v130, v19
	v_exp_f32_e32 v134, v21
	v_mul_f32_e32 v20, 0x3fb8aa3b, v20
	v_sub_f32_e32 v17, v17, v38
	v_add_f32_e32 v19, v131, v19
	v_exp_f32_e32 v135, v20
	v_mul_f32_e32 v17, 0x3fb8aa3b, v17
	v_sub_f32_e32 v16, v16, v38
	v_add_f32_e32 v19, v132, v19
	v_exp_f32_e32 v136, v17
	v_mul_f32_e32 v16, 0x3fb8aa3b, v16
	v_add_f32_e32 v19, v133, v19
	v_exp_f32_e32 v137, v16
	v_add_f32_e32 v19, v134, v19
	v_add_f32_e32 v19, v135, v19
	v_add_f32_e32 v17, v136, v19
	v_add_f32_e32 v16, v137, v17
	v_mov_b32_e32 v17, v16
	s_nop 1
	v_permlane16_swap_b32_e32 v17, v16
	v_add_u32_e32 v24, v74, v28
	v_cvt_pk_bf16_f32 v19, v55, v59
	v_add_u32_e32 v28, v24, v75
	v_add_u32_e32 v55, v24, v76
	s_waitcnt lgkmcnt(0)
	v_add_f32_e32 v39, v16, v17
	v_cvt_pk_bf16_f32 v16, v18, v22
	v_cvt_pk_bf16_f32 v17, v23, v26
	v_cvt_pk_bf16_f32 v18, v27, v56
	ds_read2st64_b64 v[20:23], v28 offset1:4
	ds_read2st64_b64 v[24:27], v55 offset1:4
	v_mov_b32_e32 v54, v39
	s_nop 1
	v_permlane32_swap_b32_e32 v54, v39
	s_waitcnt lgkmcnt(1)
	v_mov_b32_e32 v58, v20
	s_waitcnt lgkmcnt(0)
	v_mov_b32_e32 v60, v24
	v_mov_b32_e32 v61, v25
	v_mov_b32_e32 v24, v22
	v_mov_b32_e32 v25, v23
	v_mov_b32_e32 v59, v21
	v_add_f32_e32 v54, v39, v54
	v_mfma_f32_16x16x32_bf16 v[20:23], v[24:27], v[16:19], 0
	ds_read2st64_b64 v[24:27], v28 offset0:8 offset1:12
	ds_read2st64_b64 v[62:65], v55 offset0:8 offset1:12
	v_add_u32_e32 v28, v74, v29
	v_add_u32_e32 v29, v28, v75
	v_add_u32_e32 v28, v28, v76
	s_waitcnt lgkmcnt(1)
	v_mov_b32_e32 v104, v24
	v_mov_b32_e32 v105, v25
	s_waitcnt lgkmcnt(0)
	v_mov_b32_e32 v106, v62
	v_mov_b32_e32 v107, v63
	v_mov_b32_e32 v62, v26
	v_mov_b32_e32 v63, v27
	v_mfma_f32_16x16x32_bf16 v[58:61], v[58:61], v[16:19], 0
	ds_read2st64_b64 v[108:111], v28 offset1:4
	v_cvt_pk_bf16_f32 v24, v116, v117
	v_cvt_pk_bf16_f32 v25, v118, v119
	v_mfma_f32_16x16x32_bf16 v[104:107], v[104:107], v[16:19], 0
	v_cvt_pk_bf16_f32 v26, v67, v66
	s_waitcnt lgkmcnt(0)
	v_mov_b32_e32 v114, v108
	v_mov_b32_e32 v115, v109
	v_mfma_f32_16x16x32_bf16 v[16:19], v[62:65], v[16:19], 0
	ds_read2st64_b64 v[62:65], v29 offset1:4
	v_cvt_pk_bf16_f32 v27, v120, v121
	s_waitcnt lgkmcnt(0)
	v_mov_b32_e32 v108, v64
	v_mov_b32_e32 v109, v65
	v_mov_b32_e32 v112, v62
	v_mov_b32_e32 v113, v63
	v_mfma_f32_16x16x32_bf16 v[20:23], v[108:111], v[24:27], v[20:23]
	ds_read2st64_b64 v[62:65], v29 offset0:8 offset1:12
	ds_read2st64_b64 v[108:111], v28 offset0:8 offset1:12
	v_add_u32_e32 v28, v74, v30
	v_add_u32_e32 v29, v28, v75
	v_mfma_f32_16x16x32_bf16 v[58:61], v[112:115], v[24:27], v[58:61]
	v_add_u32_e32 v28, v28, v76
	s_waitcnt lgkmcnt(0)
	v_mov_b32_e32 v114, v108
	v_mov_b32_e32 v115, v109
	v_mov_b32_e32 v108, v64
	v_mov_b32_e32 v109, v65
	v_mov_b32_e32 v112, v62
	v_mov_b32_e32 v113, v63
	v_mfma_f32_16x16x32_bf16 v[16:19], v[108:111], v[24:27], v[16:19]
	ds_read2st64_b64 v[62:65], v29 offset1:4
	ds_read2st64_b64 v[108:111], v28 offset1:4
	v_mfma_f32_16x16x32_bf16 v[104:107], v[112:115], v[24:27], v[104:107]
	v_cvt_pk_bf16_f32 v24, v122, v123
	v_cvt_pk_bf16_f32 v25, v124, v125
	s_waitcnt lgkmcnt(0)
	v_mov_b32_e32 v114, v108
	v_mov_b32_e32 v115, v109
	v_mov_b32_e32 v108, v64
	v_mov_b32_e32 v109, v65
	v_cvt_pk_bf16_f32 v26, v126, v127
	v_cvt_pk_bf16_f32 v27, v128, v129
	v_mov_b32_e32 v112, v62
	v_mov_b32_e32 v113, v63
	v_mfma_f32_16x16x32_bf16 v[20:23], v[108:111], v[24:27], v[20:23]
	ds_read2st64_b64 v[62:65], v29 offset0:8 offset1:12
	ds_read2st64_b64 v[108:111], v28 offset0:8 offset1:12
	v_add_u32_e32 v28, v74, v31
	v_add_u32_e32 v55, v28, v75
	v_mfma_f32_16x16x32_bf16 v[58:61], v[112:115], v[24:27], v[58:61]
	s_waitcnt lgkmcnt(1)
	v_mov_b32_e32 v112, v62
	v_mov_b32_e32 v113, v63
	s_waitcnt lgkmcnt(0)
	v_mov_b32_e32 v114, v108
	v_mov_b32_e32 v115, v109
	v_mov_b32_e32 v108, v64
	v_mov_b32_e32 v109, v65
	v_add_u32_e32 v56, v28, v76
	v_mfma_f32_16x16x32_bf16 v[104:107], v[112:115], v[24:27], v[104:107]
	v_cvt_pk_bf16_f32 v62, v130, v131
	v_cvt_pk_bf16_f32 v63, v132, v133
	v_cvt_pk_bf16_f32 v64, v134, v135
	v_mfma_f32_16x16x32_bf16 v[16:19], v[108:111], v[24:27], v[16:19]
	ds_read2st64_b64 v[24:27], v55 offset1:4
	ds_read2st64_b64 v[108:111], v56 offset1:4
	v_cvt_pk_bf16_f32 v65, v136, v137
	s_waitcnt lgkmcnt(1)
	v_mov_b32_e32 v28, v24
	v_mov_b32_e32 v29, v25
	s_waitcnt lgkmcnt(0)
	v_mov_b32_e32 v30, v108
	v_mov_b32_e32 v31, v109
	v_mov_b32_e32 v108, v26
	v_mov_b32_e32 v109, v27
	v_mfma_f32_16x16x32_bf16 v[28:31], v[28:31], v[62:65], v[58:61]
	s_nop 0
	v_mfma_f32_16x16x32_bf16 v[24:27], v[108:111], v[62:65], v[20:23]
	s_nop 0
	ds_read2st64_b64 v[58:61], v55 offset0:8 offset1:12
	ds_read2st64_b64 v[108:111], v56 offset0:8 offset1:12
	s_waitcnt lgkmcnt(1)
	v_mov_b32_e32 v20, v58
	v_mov_b32_e32 v21, v59
	s_waitcnt lgkmcnt(0)
	v_mov_b32_e32 v22, v108
	v_mov_b32_e32 v23, v109
	v_mov_b32_e32 v108, v60
	v_mov_b32_e32 v109, v61
	v_mfma_f32_16x16x32_bf16 v[20:23], v[20:23], v[62:65], v[104:107]
	s_nop 0
	v_mfma_f32_16x16x32_bf16 v[16:19], v[108:111], v[62:65], v[16:19]
	s_and_saveexec_b64 s[0:1], s[42:43]
	s_cbranch_execz .LBB0_403
; DI void na_phase(LAS unsigned char* lds, const Args& A, const bf16* proj, bf16* nao, int T, int nB, unsigned* counter, int tid_in) {
;     ...
;             if (kh == 1) { MG[0] = mx; MG[64] = lsum;
; #pragma unroll
;                 for (int mt = 0; mt < 4; ++mt)
; #pragma unroll
;                     for (int e = 0; e < 4; ++e) MG[(2 + mt * 4 + e) * 64] = O[mt][e]; }
	ds_write2st64_b32 v103, v38, v54 offset1:1
	ds_write2st64_b32 v103, v28, v29 offset0:2 offset1:3
	ds_write2st64_b32 v103, v30, v31 offset0:4 offset1:5
	ds_write2st64_b32 v103, v24, v25 offset0:6 offset1:7
	ds_write2st64_b32 v103, v26, v27 offset0:8 offset1:9
	ds_write2st64_b32 v103, v20, v21 offset0:10 offset1:11
	ds_write2st64_b32 v103, v22, v23 offset0:12 offset1:13
	ds_write2st64_b32 v103, v16, v17 offset0:14 offset1:15
	ds_write2st64_b32 v103, v18, v19 offset0:16 offset1:17
